# plus: phase-0 cache conversion and input-row prep rewritten with batched 16-byte loads and next-row prefetch; FFN1 (relu2) GEMM epilogue loads its 8 per-row rstd values once up front instead of a load
# speedup vs baseline: 1.0611x; 1.0031x over previous
; DI bf16* xb_row(float* outp, int m) { return (bf16*)((char*)outp + (size_t)m * 8192 + 4096); }
; #define CVT_A_ST(va, vb) *(u32x4*)((bf16*)(ws + (isv##va ? A_VS : A_KS)) + (g##va / (512 * 256)) * 576 * 2048 + (g##va % (512 * 256)) * 8) = pack8(va, vb)
; __global__ void __launch_bounds__(512) fwd_mega(Args a_) {
;     ...
;         { const size_t ng = (size_t)16 * 512 * 256;
;     ...
;           size_t i = gt;
;           for (; i + 3 * NGT < 2 * ng; i += 4 * NGT) { CVT_A_LD(i, p0, p1); CVT_A_LD(i + NGT, q0, q1); CVT_A_LD(i + 2 * NGT, r0, r1); CVT_A_LD(i + 3 * NGT, t0, t1);
;             CVT_A_ST(p0, p1); CVT_A_ST(q0, q1); CVT_A_ST(r0, r1); CVT_A_ST(t0, t1); }
;           for (; i < 2 * ng; i += NGT) { CVT_A_LD(i, p0, p1); CVT_A_ST(p0, p1); }
;     ...
;         }
;         for (int m = gw; m < MT; m += NGW) row_x_prep(xin_row(a, m), xb_row(outp, m), (float*)(ws + A_RSTD) + m, lane);
.Lp0_entry:
	s_lshl_b32 s0, s81, 6
	v_add_u32_e32 v160, s0, v184
	v_lshlrev_b32_e32 v161, 4, v160
	v_lshlrev_b32_e32 v160, 5, v160
	s_load_dwordx4 s[4:7], s[22:23], 0x10
	s_add_u32 s2, s54, 0x1c000000
	s_addc_u32 s3, s55, 0
	s_waitcnt lgkmcnt(0)
	s_mov_b64 s[0:1], s[4:5]
	s_mov_b32 s8, 0
.Lp0_cv_loop:
	global_load_dwordx4 v[0:3], v160, s[0:1]
	global_load_dwordx4 v[4:7], v160, s[0:1] offset:16
	s_add_u32 s0, s0, 0x400000
	s_addc_u32 s1, s1, 0
	global_load_dwordx4 v[8:11], v160, s[0:1]
	global_load_dwordx4 v[12:15], v160, s[0:1] offset:16
	s_add_u32 s0, s0, 0x400000
	s_addc_u32 s1, s1, 0
	global_load_dwordx4 v[16:19], v160, s[0:1]
	global_load_dwordx4 v[20:23], v160, s[0:1] offset:16
	s_add_u32 s0, s0, 0x400000
	s_addc_u32 s1, s1, 0
	global_load_dwordx4 v[24:27], v160, s[0:1]
	global_load_dwordx4 v[28:31], v160, s[0:1] offset:16
	s_add_u32 s0, s0, 0x400000
	s_addc_u32 s1, s1, 0
	global_load_dwordx4 v[32:35], v160, s[0:1]
	global_load_dwordx4 v[36:39], v160, s[0:1] offset:16
	s_add_u32 s0, s0, 0x400000
	s_addc_u32 s1, s1, 0
	global_load_dwordx4 v[40:43], v160, s[0:1]
	global_load_dwordx4 v[44:47], v160, s[0:1] offset:16
	s_add_u32 s0, s0, 0x400000
	s_addc_u32 s1, s1, 0
	global_load_dwordx4 v[48:51], v160, s[0:1]
	global_load_dwordx4 v[52:55], v160, s[0:1] offset:16
	s_add_u32 s0, s0, 0x400000
	s_addc_u32 s1, s1, 0
	global_load_dwordx4 v[56:59], v160, s[0:1]
	global_load_dwordx4 v[60:63], v160, s[0:1] offset:16
	s_add_u32 s0, s0, 0x400000
	s_addc_u32 s1, s1, 0
	s_waitcnt vmcnt(14)
	v_cvt_pk_bf16_f32 v0, v0, v1
	v_cvt_pk_bf16_f32 v1, v2, v3
	v_cvt_pk_bf16_f32 v2, v4, v5
	v_cvt_pk_bf16_f32 v3, v6, v7
	global_store_dwordx4 v161, v[0:3], s[2:3]
	s_add_u32 s2, s2, 0x240000
	s_addc_u32 s3, s3, 0
	s_waitcnt vmcnt(13)
	v_cvt_pk_bf16_f32 v8, v8, v9
	v_cvt_pk_bf16_f32 v9, v10, v11
	v_cvt_pk_bf16_f32 v10, v12, v13
	v_cvt_pk_bf16_f32 v11, v14, v15
	global_store_dwordx4 v161, v[8:11], s[2:3]
	s_add_u32 s2, s2, 0x240000
	s_addc_u32 s3, s3, 0
	s_waitcnt vmcnt(12)
	v_cvt_pk_bf16_f32 v16, v16, v17
	v_cvt_pk_bf16_f32 v17, v18, v19
	v_cvt_pk_bf16_f32 v18, v20, v21
	v_cvt_pk_bf16_f32 v19, v22, v23
	global_store_dwordx4 v161, v[16:19], s[2:3]
	s_add_u32 s2, s2, 0x240000
	s_addc_u32 s3, s3, 0
	s_waitcnt vmcnt(11)
	v_cvt_pk_bf16_f32 v24, v24, v25
	v_cvt_pk_bf16_f32 v25, v26, v27
	v_cvt_pk_bf16_f32 v26, v28, v29
	v_cvt_pk_bf16_f32 v27, v30, v31
	global_store_dwordx4 v161, v[24:27], s[2:3]
	s_add_u32 s2, s2, 0x240000
	s_addc_u32 s3, s3, 0
	s_waitcnt vmcnt(10)
	v_cvt_pk_bf16_f32 v32, v32, v33
	v_cvt_pk_bf16_f32 v33, v34, v35
	v_cvt_pk_bf16_f32 v34, v36, v37
	v_cvt_pk_bf16_f32 v35, v38, v39
	global_store_dwordx4 v161, v[32:35], s[2:3]
	s_add_u32 s2, s2, 0x240000
	s_addc_u32 s3, s3, 0
	s_waitcnt vmcnt(9)
	v_cvt_pk_bf16_f32 v40, v40, v41
	v_cvt_pk_bf16_f32 v41, v42, v43
	v_cvt_pk_bf16_f32 v42, v44, v45
	v_cvt_pk_bf16_f32 v43, v46, v47
	global_store_dwordx4 v161, v[40:43], s[2:3]
	s_add_u32 s2, s2, 0x240000
	s_addc_u32 s3, s3, 0
	s_waitcnt vmcnt(8)
	v_cvt_pk_bf16_f32 v48, v48, v49
	v_cvt_pk_bf16_f32 v49, v50, v51
	v_cvt_pk_bf16_f32 v50, v52, v53
	v_cvt_pk_bf16_f32 v51, v54, v55
	global_store_dwordx4 v161, v[48:51], s[2:3]
	s_add_u32 s2, s2, 0x240000
	s_addc_u32 s3, s3, 0
	s_waitcnt vmcnt(7)
	v_cvt_pk_bf16_f32 v56, v56, v57
	v_cvt_pk_bf16_f32 v57, v58, v59
	v_cvt_pk_bf16_f32 v58, v60, v61
	v_cvt_pk_bf16_f32 v59, v62, v63
	global_store_dwordx4 v161, v[56:59], s[2:3]
	s_add_u32 s2, s2, 0x240000
	s_addc_u32 s3, s3, 0
	s_add_i32 s8, s8, 1
	s_cmp_eq_u32 s8, 2
	s_cbranch_scc0 .Lp0_cv_nosw
	s_mov_b64 s[0:1], s[6:7]
	s_add_u32 s2, s54, 0x1e400000
	s_addc_u32 s3, s55, 0
.Lp0_cv_nosw:
	s_cmp_lt_u32 s8, 4
	s_cbranch_scc1 .Lp0_cv_loop
	v_lshlrev_b32_e32 v162, 4, v186
	v_lshlrev_b32_e32 v163, 5, v186
	s_load_dwordx4 s[4:7], s[22:23], 0x0
	s_lshl_b32 s12, s72, 13
	s_add_u32 s2, s12, 0x1000
	s_add_u32 s2, s52, s2
	s_addc_u32 s3, s53, 0
	s_lshl_b32 s8, s72, 2
	s_add_u32 s8, s8, 0x2a210000
	s_add_u32 s8, s54, s8
	s_addc_u32 s9, s55, 0
	s_waitcnt lgkmcnt(0)
	s_add_u32 s0, s4, s12
	s_addc_u32 s1, s5, 0
	s_add_u32 s10, s0, 0x1000
	s_addc_u32 s11, s1, 0
	s_add_u32 s6, s6, s12
	s_addc_u32 s7, s7, 0
	s_mov_b32 s4, 0
	s_mov_b32 s5, 8
	s_cmpk_lt_i32 s72, 0x400
	s_cselect_b32 s5, 9, 8
	global_load_dwordx4 v[32:35], v163, s[0:1] offset:0
	global_load_dwordx4 v[36:39], v163, s[0:1] offset:16
	global_load_dwordx4 v[40:43], v163, s[0:1] offset:2048
	global_load_dwordx4 v[44:47], v163, s[0:1] offset:2064
	global_load_dwordx4 v[48:51], v163, s[10:11] offset:0
	global_load_dwordx4 v[52:55], v163, s[10:11] offset:16
	global_load_dwordx4 v[56:59], v163, s[10:11] offset:2048
	global_load_dwordx4 v[60:63], v163, s[10:11] offset:2064
.Lp0_xp_loop:
	s_cmp_eq_u32 s4, 0
	s_cbranch_scc1 .Lp0_xp_w0
	s_waitcnt vmcnt(5)
	s_branch .Lp0_xp_wd

; DI unsigned cvtpk(float lo, float hi) { unsigned r; asm volatile("v_cvt_pk_bf16_f32 %0, %1, %2" : "=v"(r) : "v"(lo), "v"(hi)); return r; }
; DI void row_x_prep(const float* xrow, bf16* xbrow, float* rstd_out, int lane) {
;   const f32x4* xr = (const f32x4*)xrow + lane;
;   f32x4 v[8]; float s = 0.f;
; #pragma unroll
;   for (int j = 0; j < 8; ++j) { v[j] = xr[64 * j]; s += (v[j].x * v[j].x + v[j].y * v[j].y) + (v[j].z * v[j].z + v[j].w * v[j].w); }
;   const float rstd = rsqrtf(wave_sum(s) * (1.f / DM) + EPS);
;   u32x2* x8 = (u32x2*)xbrow + lane;
; #pragma unroll
;   for (int j = 0; j < 8; ++j) { u32x2 w; w.x = cvtpk(v[j].x, v[j].y); w.y = cvtpk(v[j].z, v[j].w); x8[64 * j] = w; }
;   if (lane == 0) *rstd_out = rstd;
; }
.Lp0_xp_wd:
	v_mov_b32_e32 v0, v32
	v_mov_b32_e32 v1, v33
	v_mov_b32_e32 v2, v34
	v_mov_b32_e32 v3, v35
	v_mov_b32_e32 v4, v36
	v_mov_b32_e32 v5, v37
	v_mov_b32_e32 v6, v38
	v_mov_b32_e32 v7, v39
	v_mov_b32_e32 v8, v40
	v_mov_b32_e32 v9, v41
	v_mov_b32_e32 v10, v42
	v_mov_b32_e32 v11, v43
	v_mov_b32_e32 v12, v44
	v_mov_b32_e32 v13, v45
	v_mov_b32_e32 v14, v46
	v_mov_b32_e32 v15, v47
	v_mov_b32_e32 v16, v48
	v_mov_b32_e32 v17, v49
	v_mov_b32_e32 v18, v50
	v_mov_b32_e32 v19, v51
	v_mov_b32_e32 v20, v52
	v_mov_b32_e32 v21, v53
	v_mov_b32_e32 v22, v54
	v_mov_b32_e32 v23, v55
	v_mov_b32_e32 v24, v56
	v_mov_b32_e32 v25, v57
	v_mov_b32_e32 v26, v58
	v_mov_b32_e32 v27, v59
	v_mov_b32_e32 v28, v60
	v_mov_b32_e32 v29, v61
	v_mov_b32_e32 v30, v62
	v_mov_b32_e32 v31, v63
	s_add_i32 s12, s4, 1
	s_cmp_ge_u32 s12, s5
	s_cbranch_scc1 .Lp0_xp_nopref
	s_add_u32 s0, s0, 0x1000000
	s_addc_u32 s1, s1, 0
	s_cmp_eq_u32 s12, 8
	s_cbranch_scc0 .Lp0_xp_nosw
	s_mov_b64 s[0:1], s[6:7]
.Lp0_xp_nosw:
	s_add_u32 s10, s0, 0x1000
	s_addc_u32 s11, s1, 0
	global_load_dwordx4 v[32:35], v163, s[0:1] offset:0
	global_load_dwordx4 v[36:39], v163, s[0:1] offset:16
	global_load_dwordx4 v[40:43], v163, s[0:1] offset:2048
	global_load_dwordx4 v[44:47], v163, s[0:1] offset:2064
	global_load_dwordx4 v[48:51], v163, s[10:11] offset:0
	global_load_dwordx4 v[52:55], v163, s[10:11] offset:16
	global_load_dwordx4 v[56:59], v163, s[10:11] offset:2048
	global_load_dwordx4 v[60:63], v163, s[10:11] offset:2064
.Lp0_xp_nopref:
	v_mul_f32_e32 v168, v0, v0
	v_mul_f32_e32 v169, v1, v1
	v_mul_f32_e32 v170, v2, v2
	v_mul_f32_e32 v171, v3, v3
	v_fmac_f32_e32 v168, v4, v4
	v_fmac_f32_e32 v169, v5, v5
	v_fmac_f32_e32 v170, v6, v6
	v_fmac_f32_e32 v171, v7, v7
	v_fmac_f32_e32 v168, v8, v8
	v_fmac_f32_e32 v169, v9, v9
	v_fmac_f32_e32 v170, v10, v10
	v_fmac_f32_e32 v171, v11, v11
	v_fmac_f32_e32 v168, v12, v12
	v_fmac_f32_e32 v169, v13, v13
	v_fmac_f32_e32 v170, v14, v14
	v_fmac_f32_e32 v171, v15, v15
	v_fmac_f32_e32 v168, v16, v16
	v_fmac_f32_e32 v169, v17, v17
	v_fmac_f32_e32 v170, v18, v18
	v_fmac_f32_e32 v171, v19, v19
	v_fmac_f32_e32 v168, v20, v20
	v_fmac_f32_e32 v169, v21, v21
	v_fmac_f32_e32 v170, v22, v22
	v_fmac_f32_e32 v171, v23, v23
	v_fmac_f32_e32 v168, v24, v24
	v_fmac_f32_e32 v169, v25, v25
	v_fmac_f32_e32 v170, v26, v26
	v_fmac_f32_e32 v171, v27, v27
	v_fmac_f32_e32 v168, v28, v28
	v_fmac_f32_e32 v169, v29, v29
	v_fmac_f32_e32 v170, v30, v30
	v_fmac_f32_e32 v171, v31, v31
	v_add_f32_e32 v168, v168, v169
	v_add_f32_e32 v170, v170, v171
	v_add_f32_e32 v164, v168, v170
	v_cvt_pk_bf16_f32 v64, v0, v1
	v_cvt_pk_bf16_f32 v65, v2, v3
	v_cvt_pk_bf16_f32 v66, v4, v5
	v_cvt_pk_bf16_f32 v67, v6, v7
	v_cvt_pk_bf16_f32 v68, v8, v9
	v_cvt_pk_bf16_f32 v69, v10, v11
	v_cvt_pk_bf16_f32 v70, v12, v13
	v_cvt_pk_bf16_f32 v71, v14, v15
	v_cvt_pk_bf16_f32 v72, v16, v17
	v_cvt_pk_bf16_f32 v73, v18, v19
	v_cvt_pk_bf16_f32 v74, v20, v21
	v_cvt_pk_bf16_f32 v75, v22, v23
	v_cvt_pk_bf16_f32 v76, v24, v25
	v_cvt_pk_bf16_f32 v77, v26, v27
	v_cvt_pk_bf16_f32 v78, v28, v29
	v_cvt_pk_bf16_f32 v79, v30, v31
	global_store_dwordx4 v162, v[64:67], s[2:3] offset:0
	global_store_dwordx4 v162, v[68:71], s[2:3] offset:1024
	global_store_dwordx4 v162, v[72:75], s[2:3] offset:2048
	global_store_dwordx4 v162, v[76:79], s[2:3] offset:3072
	ds_swizzle_b32 v165, v164 offset:swizzle(SWAP,1)
	s_waitcnt lgkmcnt(0)
	v_add_f32_e32 v164, v164, v165
	ds_swizzle_b32 v165, v164 offset:swizzle(SWAP,2)
	s_waitcnt lgkmcnt(0)
	v_add_f32_e32 v164, v164, v165
	ds_swizzle_b32 v165, v164 offset:swizzle(SWAP,4)
	s_waitcnt lgkmcnt(0)
	v_add_f32_e32 v164, v164, v165
	ds_swizzle_b32 v165, v164 offset:swizzle(SWAP,8)
	s_waitcnt lgkmcnt(0)
	v_add_f32_e32 v164, v164, v165
	ds_swizzle_b32 v165, v164 offset:swizzle(SWAP,16)
	s_waitcnt lgkmcnt(0)
	v_add_f32_e32 v164, v164, v165
	v_mov_b32_e32 v165, v164
	s_nop 1
	v_permlane32_swap_b32_e32 v164, v165
	v_add_f32_e32 v164, v164, v165
	v_fmamk_f32 v166, v164, 0x3a000000, v180
	v_rsq_f32_e32 v166, v166
	s_nop 0
	s_mov_b64 exec, 1
	global_store_dword v113, v166, s[8:9]
	s_mov_b64 exec, -1
	s_nop 1
	s_add_u32 s2, s2, 0x1000000
	s_addc_u32 s3, s3, 0
	s_add_u32 s8, s8, 0x2000
	s_addc_u32 s9, s9, 0
	s_add_i32 s4, s4, 1
	s_cmp_lt_u32 s4, s5
	s_cbranch_scc1 .Lp0_xp_loop
	s_mov_b64 exec, -1
	s_branch .LBB0_451

; #define CVT_A_ST(va, vb) *(u32x4*)((bf16*)(ws + (isv##va ? A_VS : A_KS)) + (g##va / (512 * 256)) * 576 * 2048 + (g##va % (512 * 256)) * 8) = pack8(va, vb)
; __global__ void __launch_bounds__(512) fwd_mega(Args a_) {
;     ...
;       if (ph == 0) {
;         for (int it = gw; it < 32 * 96; it += NGW) transpose_item<0>(a.in[10], 2048, 6144, (bf16*)(ws + W_QKV), 0, scr, it, lane, a.in[6]);
;         { u32x4* z = (u32x4*)((bf16*)(ws + W_D) + (size_t)1088 * 2048); const size_t n16 = (size_t)192 * 2048 * 2 / 16;
;           u32x4 zv = {0u, 0u, 0u, 0u}; asm volatile("" : "+v"(zv));
;           for (size_t i = gt; i < n16; i += NGT) z[i] = zv; }
;         { const size_t ng = (size_t)16 * 512 * 256;
;     ...
;           size_t i = gt;
;           for (; i + 3 * NGT < 2 * ng; i += 4 * NGT) { CVT_A_LD(i, p0, p1); CVT_A_LD(i + NGT, q0, q1); CVT_A_LD(i + 2 * NGT, r0, r1); CVT_A_LD(i + 3 * NGT, t0, t1);
;             CVT_A_ST(p0, p1); CVT_A_ST(q0, q1); CVT_A_ST(r0, r1); CVT_A_ST(t0, t1); }
;           for (; i < 2 * ng; i += NGT) { CVT_A_LD(i, p0, p1); CVT_A_ST(p0, p1); }
.LBB0_439:
	s_or_b64 exec, exec, s[6:7]
	s_and_b64 vcc, exec, s[78:79]
	s_cbranch_vccnz .Lp0_entry
	v_readlane_b32 s0, v255, 26
	v_readlane_b32 s1, v255, 27
	s_nop 1
	v_lshl_add_u64 v[0:1], v[188:189], 0, s[0:1]
	s_mov_b64 s[0:1], 0x400000
	v_cmp_gt_u64_e32 vcc, s[0:1], v[0:1]
	s_and_saveexec_b64 s[6:7], vcc
	s_cbranch_execz .LBB0_443
	v_readlane_b32 s2, v255, 18
	v_readlane_b32 s4, v255, 26
	s_mov_b32 s14, 0xffe00000
	s_mov_b64 s[8:9], 0
	v_readlane_b32 s3, v255, 19
	v_readlane_b32 s5, v255, 27
	s_mov_b32 s10, 0x240000
	s_mov_b64 s[12:13], 0x1fffff
	s_mov_b32 s15, -1
	s_mov_b64 s[16:17], 0x3fffff

; DI u32x4 pack8(f32x4 a, f32x4 b) { u32x4 w; w.x = cvtpk(a.x, a.y); w.y = cvtpk(a.z, a.w); w.z = cvtpk(b.x, b.y); w.w = cvtpk(b.z, b.w); return w; }
;   template <int MODE> DI void store8(int row, int col, f32x4 v0, f32x4 v1, int part) const {
;     if (MODE == EM_QKV || MODE == EM_RELU2 || MODE == EM_F32) { const float r_ = rs[row]; v0 *= r_; v1 *= r_; }
;     if (MODE == EM_TAIL) {
;       if (part >= 16) *(u32x4*)(O2 + ((size_t)(part - 16) * 1024 + (row - NPR)) * 2048 + col) = pack8(v0, v1);
;       else *(u32x4*)(O + (size_t)row * ldc + col) = pack8(v0, v1);
;     } else if (MODE == EM_SPLIT) {
;       bf16* d = (part & 1) ? O2 : O; *(u32x4*)(d + (size_t)row * ldc + col) = pack8(v0, v1);
;       if (part & 2) *(u32x4*)(O2 + (size_t)row * ldc + col) = (u32x4){0u, 0u, 0u, 0u};
;     } else if (MODE == EM_BF16) { *(u32x4*)(O + (size_t)row * ldc + col) = pack8(v0, v1); }
;     else if (MODE == EM_RELU2) {
;       f32x4 a = __builtin_elementwise_max(v0, (f32x4){0.f, 0.f, 0.f, 0.f}), b = __builtin_elementwise_max(v1, (f32x4){0.f, 0.f, 0.f, 0.f});
;       *(u32x4*)(O + (size_t)row * ldc + col) = pack8(a * a, b * b); }
;   template <int MODE> DI void run(const f32x4 (&acc)[2][2][4][2], const pg8::Unit& u, int wr, int wc, int fr, int fq) const {
; #pragma unroll
;     for (int ai = 0; ai < 2; ++ai)
; #pragma unroll
;       for (int m = 0; m < 4; ++m) {
;         const int row = u.pm * 256 + ai * 128 + wr * 64 + m * 16 + fr;
; #pragma unroll
;         for (int bj = 0; bj < 2; ++bj) { store8<MODE>(row, u.pn * 256 + bj * 128 + wc * 32 + 8 * fq, acc[ai][bj][m][0], acc[ai][bj][m][1], u.part);
;           if (MODE == EM_QROPE || MODE == EM_QKV) asm volatile("" ::: "memory"); }
;       }
;   }
.LBB0_668:
	s_andn2_b64 vcc, exec, s[20:21]
	s_cbranch_vccnz .LBB0_837
	s_cmp_lt_i32 s71, 1
	s_mov_b64 s[20:21], -1
	s_cbranch_scc1 .LBB0_835
	s_cmp_gt_i32 s71, 1
	s_cbranch_scc0 .LBB0_672
	v_or_b32_e32 v112, s78, v179
	v_lshl_add_u32 v132, s83, 8, v112
	v_ashrrev_i32_e32 v133, 31, v132
	s_lshl_b32 s20, s66, 8
	v_lshl_or_b32 v112, v178, 3, s20
	v_lshl_add_u64 v[134:135], v[132:133], 2, s[96:97]
	v_or_b32_e32 v130, s79, v112
	global_load_dword v188, v[134:135], off
	global_load_dword v189, v[134:135], off offset:64
	global_load_dword v190, v[134:135], off offset:128
	global_load_dword v191, v[134:135], off offset:192
	global_load_dword v192, v[134:135], off offset:512
	global_load_dword v193, v[134:135], off offset:576
	global_load_dword v194, v[134:135], off offset:640
	global_load_dword v195, v[134:135], off offset:704
	v_mul_lo_u32 v131, s89, v132
	s_waitcnt vmcnt(0)
	v_mov_b32_e32 v112, v188
	v_pk_mul_f32 v[136:137], v[128:129], v[112:113] op_sel_hi:[1,0]
	v_pk_mul_f32 v[138:139], v[126:127], v[112:113] op_sel_hi:[1,0]
	v_pk_mul_f32 v[140:141], v[124:125], v[112:113] op_sel_hi:[1,0]
	v_pk_mul_f32 v[154:155], v[122:123], v[112:113] op_sel_hi:[1,0]
	v_max_f32_e32 v139, 0, v139
	v_max_f32_e32 v138, 0, v138
	v_max_f32_e32 v137, 0, v137
	v_max_f32_e32 v136, 0, v136
	v_max_f32_e32 v155, 0, v155
	v_max_f32_e32 v154, 0, v154
	v_max_f32_e32 v141, 0, v141
	v_max_f32_e32 v140, 0, v140
	v_pk_mul_f32 v[156:157], v[136:137], v[136:137]
	v_pk_mul_f32 v[136:137], v[138:139], v[138:139]
	v_pk_mul_f32 v[140:141], v[140:141], v[140:141]
	v_pk_mul_f32 v[138:139], v[154:155], v[154:155]
	v_cvt_pk_bf16_f32 v136, v136, v137
	v_cvt_pk_bf16_f32 v137, v156, v157
	v_mul_lo_u32 v112, s88, v133
	v_cvt_pk_bf16_f32 v138, v138, v139
	v_cvt_pk_bf16_f32 v139, v140, v141
	v_mad_u64_u32 v[140:141], s[20:21], s88, v132, 0
	v_add3_u32 v141, v141, v112, v131
	v_ashrrev_i32_e32 v131, 31, v130
	v_lshl_add_u64 v[140:141], v[140:141], 1, s[90:91]
	v_lshlrev_b64 v[130:131], 1, v[130:131]
	v_lshl_add_u64 v[140:141], v[140:141], 0, v[130:131]
	global_store_dwordx4 v[140:141], v[136:139], off
	v_mov_b32_e32 v112, v188
	v_pk_mul_f32 v[134:135], v[120:121], v[112:113] op_sel_hi:[1,0]
	v_pk_mul_f32 v[136:137], v[118:119], v[112:113] op_sel_hi:[1,0]
	v_pk_mul_f32 v[154:155], v[114:115], v[112:113] op_sel_hi:[1,0]
	v_pk_mul_f32 v[138:139], v[116:117], v[112:113] op_sel_hi:[1,0]
	v_max_f32_e32 v137, 0, v137
	v_max_f32_e32 v136, 0, v136
	v_max_f32_e32 v135, 0, v135
	v_max_f32_e32 v134, 0, v134
	v_max_f32_e32 v155, 0, v155
	v_max_f32_e32 v154, 0, v154
	v_max_f32_e32 v139, 0, v139
	v_max_f32_e32 v138, 0, v138
	v_pk_mul_f32 v[156:157], v[134:135], v[134:135]
	v_pk_mul_f32 v[134:135], v[136:137], v[136:137]
	v_pk_mul_f32 v[136:137], v[154:155], v[154:155]
	v_pk_mul_f32 v[138:139], v[138:139], v[138:139]
	v_cvt_pk_bf16_f32 v134, v134, v135
	v_cvt_pk_bf16_f32 v135, v156, v157
	v_cvt_pk_bf16_f32 v136, v136, v137
	s_nop 0
	v_cvt_pk_bf16_f32 v137, v138, v139
	global_store_dwordx4 v[140:141], v[134:137], off offset:256
	v_or_b32_e32 v140, 16, v132
	v_ashrrev_i32_e32 v141, 31, v140
	v_lshl_add_u64 v[134:135], v[140:141], 2, s[96:97]
	v_mov_b32_e32 v112, v189
	v_mul_lo_u32 v133, s89, v140
	v_pk_mul_f32 v[136:137], v[110:111], v[112:113] op_sel_hi:[1,0]
	v_pk_mul_f32 v[138:139], v[108:109], v[112:113] op_sel_hi:[1,0]
	v_pk_mul_f32 v[154:155], v[106:107], v[112:113] op_sel_hi:[1,0]
	v_pk_mul_f32 v[156:157], v[104:105], v[112:113] op_sel_hi:[1,0]
	v_mul_lo_u32 v112, s88, v141
	v_mad_u64_u32 v[140:141], s[20:21], s88, v140, 0
	v_add3_u32 v141, v141, v112, v133
	v_max_f32_e32 v139, 0, v139
	v_max_f32_e32 v138, 0, v138
	v_max_f32_e32 v137, 0, v137
	v_max_f32_e32 v136, 0, v136
	v_max_f32_e32 v157, 0, v157
	v_max_f32_e32 v156, 0, v156
	v_lshl_add_u64 v[140:141], v[140:141], 1, s[90:91]
	v_max_f32_e32 v155, 0, v155
	v_max_f32_e32 v154, 0, v154
	v_pk_mul_f32 v[158:159], v[136:137], v[136:137]
	v_pk_mul_f32 v[136:137], v[138:139], v[138:139]
	v_pk_mul_f32 v[138:139], v[156:157], v[156:157]
	v_lshl_add_u64 v[140:141], v[140:141], 0, v[130:131]
	v_pk_mul_f32 v[154:155], v[154:155], v[154:155]
	v_cvt_pk_bf16_f32 v136, v136, v137
	v_cvt_pk_bf16_f32 v137, v158, v159
	v_cvt_pk_bf16_f32 v138, v138, v139
	s_nop 0
	v_cvt_pk_bf16_f32 v139, v154, v155
	global_store_dwordx4 v[140:141], v[136:139], off
	v_mov_b32_e32 v112, v189
	v_pk_mul_f32 v[134:135], v[102:103], v[112:113] op_sel_hi:[1,0]
	v_pk_mul_f32 v[136:137], v[100:101], v[112:113] op_sel_hi:[1,0]
	v_pk_mul_f32 v[154:155], v[96:97], v[112:113] op_sel_hi:[1,0]
	v_pk_mul_f32 v[138:139], v[98:99], v[112:113] op_sel_hi:[1,0]
	v_max_f32_e32 v137, 0, v137
	v_max_f32_e32 v136, 0, v136
	v_max_f32_e32 v135, 0, v135
	v_max_f32_e32 v134, 0, v134
	v_max_f32_e32 v155, 0, v155
	v_max_f32_e32 v154, 0, v154
	v_max_f32_e32 v139, 0, v139
	v_max_f32_e32 v138, 0, v138
	v_pk_mul_f32 v[156:157], v[134:135], v[134:135]
	v_pk_mul_f32 v[134:135], v[136:137], v[136:137]
	v_pk_mul_f32 v[136:137], v[154:155], v[154:155]
	v_pk_mul_f32 v[138:139], v[138:139], v[138:139]
	v_cvt_pk_bf16_f32 v134, v134, v135
	v_cvt_pk_bf16_f32 v135, v156, v157
	v_cvt_pk_bf16_f32 v136, v136, v137
	s_nop 0
	v_cvt_pk_bf16_f32 v137, v138, v139
	global_store_dwordx4 v[140:141], v[134:137], off offset:256
	v_or_b32_e32 v140, 32, v132
	v_ashrrev_i32_e32 v141, 31, v140
	v_lshl_add_u64 v[134:135], v[140:141], 2, s[96:97]
	v_mov_b32_e32 v112, v190
	v_mul_lo_u32 v133, s89, v140
	v_pk_mul_f32 v[136:137], v[94:95], v[112:113] op_sel_hi:[1,0]
	v_pk_mul_f32 v[138:139], v[92:93], v[112:113] op_sel_hi:[1,0]
	v_pk_mul_f32 v[154:155], v[90:91], v[112:113] op_sel_hi:[1,0]
	v_pk_mul_f32 v[156:157], v[88:89], v[112:113] op_sel_hi:[1,0]
; DI u32x4 pack8(f32x4 a, f32x4 b) { u32x4 w; w.x = cvtpk(a.x, a.y); w.y = cvtpk(a.z, a.w); w.z = cvtpk(b.x, b.y); w.w = cvtpk(b.z, b.w); return w; }
;   template <int MODE> DI void store8(int row, int col, f32x4 v0, f32x4 v1, int part) const {
;     if (MODE == EM_QKV || MODE == EM_RELU2 || MODE == EM_F32) { const float r_ = rs[row]; v0 *= r_; v1 *= r_; }
;     if (MODE == EM_TAIL) {
;       if (part >= 16) *(u32x4*)(O2 + ((size_t)(part - 16) * 1024 + (row - NPR)) * 2048 + col) = pack8(v0, v1);
;       else *(u32x4*)(O + (size_t)row * ldc + col) = pack8(v0, v1);
;     } else if (MODE == EM_SPLIT) {
;       bf16* d = (part & 1) ? O2 : O; *(u32x4*)(d + (size_t)row * ldc + col) = pack8(v0, v1);
;       if (part & 2) *(u32x4*)(O2 + (size_t)row * ldc + col) = (u32x4){0u, 0u, 0u, 0u};
;     } else if (MODE == EM_BF16) { *(u32x4*)(O + (size_t)row * ldc + col) = pack8(v0, v1); }
;     else if (MODE == EM_RELU2) {
;       f32x4 a = __builtin_elementwise_max(v0, (f32x4){0.f, 0.f, 0.f, 0.f}), b = __builtin_elementwise_max(v1, (f32x4){0.f, 0.f, 0.f, 0.f});
;       *(u32x4*)(O + (size_t)row * ldc + col) = pack8(a * a, b * b); }
;   template <int MODE> DI void run(const f32x4 (&acc)[2][2][4][2], const pg8::Unit& u, int wr, int wc, int fr, int fq) const {
; #pragma unroll
;     for (int ai = 0; ai < 2; ++ai)
; #pragma unroll
;       for (int m = 0; m < 4; ++m) {
;         const int row = u.pm * 256 + ai * 128 + wr * 64 + m * 16 + fr;
; #pragma unroll
;         for (int bj = 0; bj < 2; ++bj) { store8<MODE>(row, u.pn * 256 + bj * 128 + wc * 32 + 8 * fq, acc[ai][bj][m][0], acc[ai][bj][m][1], u.part);
;           if (MODE == EM_QROPE || MODE == EM_QKV) asm volatile("" ::: "memory"); }
;       }
;   }
	v_mul_lo_u32 v112, s88, v141
	v_mad_u64_u32 v[140:141], s[20:21], s88, v140, 0
	v_add3_u32 v141, v141, v112, v133
	v_max_f32_e32 v139, 0, v139
	v_max_f32_e32 v138, 0, v138
	v_max_f32_e32 v137, 0, v137
	v_max_f32_e32 v136, 0, v136
	v_max_f32_e32 v157, 0, v157
	v_max_f32_e32 v156, 0, v156
	v_lshl_add_u64 v[140:141], v[140:141], 1, s[90:91]
	v_max_f32_e32 v155, 0, v155
	v_max_f32_e32 v154, 0, v154
	v_pk_mul_f32 v[158:159], v[136:137], v[136:137]
	v_pk_mul_f32 v[136:137], v[138:139], v[138:139]
	v_pk_mul_f32 v[138:139], v[156:157], v[156:157]
	v_lshl_add_u64 v[140:141], v[140:141], 0, v[130:131]
	v_pk_mul_f32 v[154:155], v[154:155], v[154:155]
	v_cvt_pk_bf16_f32 v136, v136, v137
	v_cvt_pk_bf16_f32 v137, v158, v159
	v_cvt_pk_bf16_f32 v138, v138, v139
	s_nop 0
	v_cvt_pk_bf16_f32 v139, v154, v155
	global_store_dwordx4 v[140:141], v[136:139], off
	v_mov_b32_e32 v112, v190
	v_pk_mul_f32 v[134:135], v[86:87], v[112:113] op_sel_hi:[1,0]
	v_pk_mul_f32 v[136:137], v[84:85], v[112:113] op_sel_hi:[1,0]
	v_pk_mul_f32 v[154:155], v[80:81], v[112:113] op_sel_hi:[1,0]
	v_pk_mul_f32 v[138:139], v[82:83], v[112:113] op_sel_hi:[1,0]
	v_max_f32_e32 v137, 0, v137
	v_max_f32_e32 v136, 0, v136
	v_max_f32_e32 v135, 0, v135
	v_max_f32_e32 v134, 0, v134
	v_max_f32_e32 v155, 0, v155
	v_max_f32_e32 v154, 0, v154
	v_max_f32_e32 v139, 0, v139
	v_max_f32_e32 v138, 0, v138
	v_pk_mul_f32 v[156:157], v[134:135], v[134:135]
	v_pk_mul_f32 v[134:135], v[136:137], v[136:137]
	v_pk_mul_f32 v[136:137], v[154:155], v[154:155]
	v_pk_mul_f32 v[138:139], v[138:139], v[138:139]
	v_cvt_pk_bf16_f32 v134, v134, v135
	v_cvt_pk_bf16_f32 v135, v156, v157
	v_cvt_pk_bf16_f32 v136, v136, v137
	s_nop 0
	v_cvt_pk_bf16_f32 v137, v138, v139
	global_store_dwordx4 v[140:141], v[134:137], off offset:256
	v_or_b32_e32 v140, 48, v132
	v_ashrrev_i32_e32 v141, 31, v140
	v_lshl_add_u64 v[134:135], v[140:141], 2, s[96:97]
	v_mov_b32_e32 v112, v191
	v_mul_lo_u32 v133, s89, v140
	v_pk_mul_f32 v[136:137], v[78:79], v[112:113] op_sel_hi:[1,0]
	v_pk_mul_f32 v[138:139], v[76:77], v[112:113] op_sel_hi:[1,0]
	v_pk_mul_f32 v[154:155], v[74:75], v[112:113] op_sel_hi:[1,0]
	v_pk_mul_f32 v[156:157], v[72:73], v[112:113] op_sel_hi:[1,0]
	v_mul_lo_u32 v112, s88, v141
	v_mad_u64_u32 v[140:141], s[20:21], s88, v140, 0
	v_add3_u32 v141, v141, v112, v133
	v_max_f32_e32 v139, 0, v139
	v_max_f32_e32 v138, 0, v138
	v_max_f32_e32 v137, 0, v137
	v_max_f32_e32 v136, 0, v136
	v_max_f32_e32 v157, 0, v157
	v_max_f32_e32 v156, 0, v156
	v_lshl_add_u64 v[140:141], v[140:141], 1, s[90:91]
	v_max_f32_e32 v155, 0, v155
	v_max_f32_e32 v154, 0, v154
	v_pk_mul_f32 v[158:159], v[136:137], v[136:137]
	v_pk_mul_f32 v[136:137], v[138:139], v[138:139]
	v_pk_mul_f32 v[138:139], v[156:157], v[156:157]
	v_lshl_add_u64 v[140:141], v[140:141], 0, v[130:131]
	v_pk_mul_f32 v[154:155], v[154:155], v[154:155]
	v_cvt_pk_bf16_f32 v136, v136, v137
	v_cvt_pk_bf16_f32 v137, v158, v159
	v_cvt_pk_bf16_f32 v138, v138, v139
	s_nop 0
	v_cvt_pk_bf16_f32 v139, v154, v155
	global_store_dwordx4 v[140:141], v[136:139], off
	v_mov_b32_e32 v112, v191
	v_pk_mul_f32 v[134:135], v[70:71], v[112:113] op_sel_hi:[1,0]
	v_pk_mul_f32 v[136:137], v[68:69], v[112:113] op_sel_hi:[1,0]
	v_pk_mul_f32 v[154:155], v[64:65], v[112:113] op_sel_hi:[1,0]
	v_pk_mul_f32 v[138:139], v[66:67], v[112:113] op_sel_hi:[1,0]
	v_max_f32_e32 v137, 0, v137
	v_max_f32_e32 v136, 0, v136
	v_max_f32_e32 v135, 0, v135
	v_max_f32_e32 v134, 0, v134
	v_max_f32_e32 v155, 0, v155
	v_max_f32_e32 v154, 0, v154
	v_max_f32_e32 v139, 0, v139
	v_max_f32_e32 v138, 0, v138
	v_pk_mul_f32 v[156:157], v[134:135], v[134:135]
	v_pk_mul_f32 v[134:135], v[136:137], v[136:137]
	v_pk_mul_f32 v[136:137], v[154:155], v[154:155]
	v_pk_mul_f32 v[138:139], v[138:139], v[138:139]
	v_cvt_pk_bf16_f32 v134, v134, v135
	v_cvt_pk_bf16_f32 v135, v156, v157
	v_cvt_pk_bf16_f32 v136, v136, v137
	s_nop 0
	v_cvt_pk_bf16_f32 v137, v138, v139
	global_store_dwordx4 v[140:141], v[134:137], off offset:256
	v_add_u32_e32 v140, 0x80, v132
	v_ashrrev_i32_e32 v141, 31, v140
	v_lshl_add_u64 v[134:135], v[140:141], 2, s[96:97]
	v_mov_b32_e32 v112, v192
	v_mul_lo_u32 v133, s89, v140
	v_pk_mul_f32 v[136:137], v[62:63], v[112:113] op_sel_hi:[1,0]
	v_pk_mul_f32 v[138:139], v[60:61], v[112:113] op_sel_hi:[1,0]
	v_pk_mul_f32 v[154:155], v[58:59], v[112:113] op_sel_hi:[1,0]
	v_pk_mul_f32 v[156:157], v[56:57], v[112:113] op_sel_hi:[1,0]
	v_mul_lo_u32 v112, s88, v141
	v_mad_u64_u32 v[140:141], s[20:21], s88, v140, 0
	v_add3_u32 v141, v141, v112, v133
	v_max_f32_e32 v139, 0, v139
	v_max_f32_e32 v138, 0, v138
	v_max_f32_e32 v137, 0, v137
	v_max_f32_e32 v136, 0, v136
	v_max_f32_e32 v157, 0, v157
	v_max_f32_e32 v156, 0, v156
	v_lshl_add_u64 v[140:141], v[140:141], 1, s[90:91]
	v_max_f32_e32 v155, 0, v155
	v_max_f32_e32 v154, 0, v154
	v_pk_mul_f32 v[158:159], v[136:137], v[136:137]
	v_pk_mul_f32 v[136:137], v[138:139], v[138:139]
	v_pk_mul_f32 v[138:139], v[156:157], v[156:157]
	v_lshl_add_u64 v[140:141], v[140:141], 0, v[130:131]
	v_pk_mul_f32 v[154:155], v[154:155], v[154:155]
	v_cvt_pk_bf16_f32 v136, v136, v137
	v_cvt_pk_bf16_f32 v137, v158, v159
	v_cvt_pk_bf16_f32 v138, v138, v139
	s_nop 0
	v_cvt_pk_bf16_f32 v139, v154, v155
	global_store_dwordx4 v[140:141], v[136:139], off
	v_mov_b32_e32 v112, v192
	v_pk_mul_f32 v[134:135], v[54:55], v[112:113] op_sel_hi:[1,0]
	v_pk_mul_f32 v[136:137], v[52:53], v[112:113] op_sel_hi:[1,0]
	v_pk_mul_f32 v[154:155], v[48:49], v[112:113] op_sel_hi:[1,0]
	v_pk_mul_f32 v[138:139], v[50:51], v[112:113] op_sel_hi:[1,0]
	v_max_f32_e32 v137, 0, v137
	v_max_f32_e32 v136, 0, v136
	v_max_f32_e32 v135, 0, v135
	v_max_f32_e32 v134, 0, v134
; DI u32x4 pack8(f32x4 a, f32x4 b) { u32x4 w; w.x = cvtpk(a.x, a.y); w.y = cvtpk(a.z, a.w); w.z = cvtpk(b.x, b.y); w.w = cvtpk(b.z, b.w); return w; }
;   template <int MODE> DI void store8(int row, int col, f32x4 v0, f32x4 v1, int part) const {
;     if (MODE == EM_QKV || MODE == EM_RELU2 || MODE == EM_F32) { const float r_ = rs[row]; v0 *= r_; v1 *= r_; }
;     if (MODE == EM_TAIL) {
;       if (part >= 16) *(u32x4*)(O2 + ((size_t)(part - 16) * 1024 + (row - NPR)) * 2048 + col) = pack8(v0, v1);
;       else *(u32x4*)(O + (size_t)row * ldc + col) = pack8(v0, v1);
;     } else if (MODE == EM_SPLIT) {
;       bf16* d = (part & 1) ? O2 : O; *(u32x4*)(d + (size_t)row * ldc + col) = pack8(v0, v1);
;       if (part & 2) *(u32x4*)(O2 + (size_t)row * ldc + col) = (u32x4){0u, 0u, 0u, 0u};
;     } else if (MODE == EM_BF16) { *(u32x4*)(O + (size_t)row * ldc + col) = pack8(v0, v1); }
;     else if (MODE == EM_RELU2) {
;       f32x4 a = __builtin_elementwise_max(v0, (f32x4){0.f, 0.f, 0.f, 0.f}), b = __builtin_elementwise_max(v1, (f32x4){0.f, 0.f, 0.f, 0.f});
;       *(u32x4*)(O + (size_t)row * ldc + col) = pack8(a * a, b * b); }
;   template <int MODE> DI void run(const f32x4 (&acc)[2][2][4][2], const pg8::Unit& u, int wr, int wc, int fr, int fq) const {
; #pragma unroll
;     for (int ai = 0; ai < 2; ++ai)
; #pragma unroll
;       for (int m = 0; m < 4; ++m) {
;         const int row = u.pm * 256 + ai * 128 + wr * 64 + m * 16 + fr;
; #pragma unroll
;         for (int bj = 0; bj < 2; ++bj) { store8<MODE>(row, u.pn * 256 + bj * 128 + wc * 32 + 8 * fq, acc[ai][bj][m][0], acc[ai][bj][m][1], u.part);
;           if (MODE == EM_QROPE || MODE == EM_QKV) asm volatile("" ::: "memory"); }
;       }
;   }
	v_max_f32_e32 v155, 0, v155
	v_max_f32_e32 v154, 0, v154
	v_max_f32_e32 v139, 0, v139
	v_max_f32_e32 v138, 0, v138
	v_pk_mul_f32 v[156:157], v[134:135], v[134:135]
	v_pk_mul_f32 v[134:135], v[136:137], v[136:137]
	v_pk_mul_f32 v[136:137], v[154:155], v[154:155]
	v_pk_mul_f32 v[138:139], v[138:139], v[138:139]
	v_cvt_pk_bf16_f32 v134, v134, v135
	v_cvt_pk_bf16_f32 v135, v156, v157
	v_cvt_pk_bf16_f32 v136, v136, v137
	s_nop 0
	v_cvt_pk_bf16_f32 v137, v138, v139
	global_store_dwordx4 v[140:141], v[134:137], off offset:256
	v_add_u32_e32 v140, 0x90, v132
	v_ashrrev_i32_e32 v141, 31, v140
	v_lshl_add_u64 v[134:135], v[140:141], 2, s[96:97]
	v_mov_b32_e32 v112, v193
	v_mul_lo_u32 v133, s89, v140
	v_pk_mul_f32 v[136:137], v[46:47], v[112:113] op_sel_hi:[1,0]
	v_pk_mul_f32 v[138:139], v[44:45], v[112:113] op_sel_hi:[1,0]
	v_pk_mul_f32 v[154:155], v[42:43], v[112:113] op_sel_hi:[1,0]
	v_pk_mul_f32 v[156:157], v[40:41], v[112:113] op_sel_hi:[1,0]
	v_mul_lo_u32 v112, s88, v141
	v_mad_u64_u32 v[140:141], s[20:21], s88, v140, 0
	v_add3_u32 v141, v141, v112, v133
	v_max_f32_e32 v139, 0, v139
	v_max_f32_e32 v138, 0, v138
	v_max_f32_e32 v137, 0, v137
	v_max_f32_e32 v136, 0, v136
	v_max_f32_e32 v157, 0, v157
	v_max_f32_e32 v156, 0, v156
	v_lshl_add_u64 v[140:141], v[140:141], 1, s[90:91]
	v_max_f32_e32 v155, 0, v155
	v_max_f32_e32 v154, 0, v154
	v_pk_mul_f32 v[158:159], v[136:137], v[136:137]
	v_pk_mul_f32 v[136:137], v[138:139], v[138:139]
	v_pk_mul_f32 v[138:139], v[156:157], v[156:157]
	v_lshl_add_u64 v[140:141], v[140:141], 0, v[130:131]
	v_pk_mul_f32 v[154:155], v[154:155], v[154:155]
	v_cvt_pk_bf16_f32 v136, v136, v137
	v_cvt_pk_bf16_f32 v137, v158, v159
	v_cvt_pk_bf16_f32 v138, v138, v139
	s_nop 0
	v_cvt_pk_bf16_f32 v139, v154, v155
	global_store_dwordx4 v[140:141], v[136:139], off
	v_mov_b32_e32 v112, v193
	v_pk_mul_f32 v[134:135], v[38:39], v[112:113] op_sel_hi:[1,0]
	v_pk_mul_f32 v[136:137], v[36:37], v[112:113] op_sel_hi:[1,0]
	v_pk_mul_f32 v[154:155], v[32:33], v[112:113] op_sel_hi:[1,0]
	v_pk_mul_f32 v[138:139], v[34:35], v[112:113] op_sel_hi:[1,0]
	v_max_f32_e32 v137, 0, v137
	v_max_f32_e32 v136, 0, v136
	v_max_f32_e32 v135, 0, v135
	v_max_f32_e32 v134, 0, v134
	v_max_f32_e32 v155, 0, v155
	v_max_f32_e32 v154, 0, v154
	v_max_f32_e32 v139, 0, v139
	v_max_f32_e32 v138, 0, v138
	v_pk_mul_f32 v[156:157], v[134:135], v[134:135]
	v_pk_mul_f32 v[134:135], v[136:137], v[136:137]
	v_pk_mul_f32 v[136:137], v[154:155], v[154:155]
	v_pk_mul_f32 v[138:139], v[138:139], v[138:139]
	v_cvt_pk_bf16_f32 v134, v134, v135
	v_cvt_pk_bf16_f32 v135, v156, v157
	v_cvt_pk_bf16_f32 v136, v136, v137
	s_nop 0
	v_cvt_pk_bf16_f32 v137, v138, v139
	global_store_dwordx4 v[140:141], v[134:137], off offset:256
	v_add_u32_e32 v140, 0xa0, v132
	v_ashrrev_i32_e32 v141, 31, v140
	v_lshl_add_u64 v[134:135], v[140:141], 2, s[96:97]
	v_mov_b32_e32 v112, v194
	v_mul_lo_u32 v133, s89, v140
	v_pk_mul_f32 v[136:137], v[30:31], v[112:113] op_sel_hi:[1,0]
	v_pk_mul_f32 v[138:139], v[28:29], v[112:113] op_sel_hi:[1,0]
	v_pk_mul_f32 v[154:155], v[26:27], v[112:113] op_sel_hi:[1,0]
	v_pk_mul_f32 v[156:157], v[24:25], v[112:113] op_sel_hi:[1,0]
	v_mul_lo_u32 v112, s88, v141
	v_mad_u64_u32 v[140:141], s[20:21], s88, v140, 0
	v_add3_u32 v141, v141, v112, v133
	v_max_f32_e32 v139, 0, v139
	v_max_f32_e32 v138, 0, v138
	v_max_f32_e32 v137, 0, v137
	v_max_f32_e32 v136, 0, v136
	v_max_f32_e32 v157, 0, v157
	v_max_f32_e32 v156, 0, v156
	v_lshl_add_u64 v[140:141], v[140:141], 1, s[90:91]
	v_max_f32_e32 v155, 0, v155
	v_max_f32_e32 v154, 0, v154
; DI u32x4 pack8(f32x4 a, f32x4 b) { u32x4 w; w.x = cvtpk(a.x, a.y); w.y = cvtpk(a.z, a.w); w.z = cvtpk(b.x, b.y); w.w = cvtpk(b.z, b.w); return w; }
;   template <int MODE> DI void store8(int row, int col, f32x4 v0, f32x4 v1, int part) const {
;     if (MODE == EM_QKV || MODE == EM_RELU2 || MODE == EM_F32) { const float r_ = rs[row]; v0 *= r_; v1 *= r_; }
;     if (MODE == EM_TAIL) {
;       if (part >= 16) *(u32x4*)(O2 + ((size_t)(part - 16) * 1024 + (row - NPR)) * 2048 + col) = pack8(v0, v1);
;       else *(u32x4*)(O + (size_t)row * ldc + col) = pack8(v0, v1);
;     } else if (MODE == EM_SPLIT) {
;       bf16* d = (part & 1) ? O2 : O; *(u32x4*)(d + (size_t)row * ldc + col) = pack8(v0, v1);
;       if (part & 2) *(u32x4*)(O2 + (size_t)row * ldc + col) = (u32x4){0u, 0u, 0u, 0u};
;     } else if (MODE == EM_BF16) { *(u32x4*)(O + (size_t)row * ldc + col) = pack8(v0, v1); }
;     else if (MODE == EM_RELU2) {
;       f32x4 a = __builtin_elementwise_max(v0, (f32x4){0.f, 0.f, 0.f, 0.f}), b = __builtin_elementwise_max(v1, (f32x4){0.f, 0.f, 0.f, 0.f});
;       *(u32x4*)(O + (size_t)row * ldc + col) = pack8(a * a, b * b); }
;   template <int MODE> DI void run(const f32x4 (&acc)[2][2][4][2], const pg8::Unit& u, int wr, int wc, int fr, int fq) const {
; #pragma unroll
;     for (int ai = 0; ai < 2; ++ai)
; #pragma unroll
;       for (int m = 0; m < 4; ++m) {
;         const int row = u.pm * 256 + ai * 128 + wr * 64 + m * 16 + fr;
; #pragma unroll
;         for (int bj = 0; bj < 2; ++bj) { store8<MODE>(row, u.pn * 256 + bj * 128 + wc * 32 + 8 * fq, acc[ai][bj][m][0], acc[ai][bj][m][1], u.part);
;           if (MODE == EM_QROPE || MODE == EM_QKV) asm volatile("" ::: "memory"); }
;       }
;   }
	v_pk_mul_f32 v[158:159], v[136:137], v[136:137]
	v_pk_mul_f32 v[136:137], v[138:139], v[138:139]
	v_pk_mul_f32 v[138:139], v[156:157], v[156:157]
	v_lshl_add_u64 v[140:141], v[140:141], 0, v[130:131]
	v_pk_mul_f32 v[154:155], v[154:155], v[154:155]
	v_cvt_pk_bf16_f32 v136, v136, v137
	v_cvt_pk_bf16_f32 v137, v158, v159
	v_cvt_pk_bf16_f32 v138, v138, v139
	s_nop 0
	v_cvt_pk_bf16_f32 v139, v154, v155
	global_store_dwordx4 v[140:141], v[136:139], off
	v_mov_b32_e32 v112, v194
	v_pk_mul_f32 v[134:135], v[22:23], v[112:113] op_sel_hi:[1,0]
	v_pk_mul_f32 v[136:137], v[20:21], v[112:113] op_sel_hi:[1,0]
	v_pk_mul_f32 v[138:139], v[18:19], v[112:113] op_sel_hi:[1,0]
	v_pk_mul_f32 v[154:155], v[16:17], v[112:113] op_sel_hi:[1,0]
	v_max_f32_e32 v137, 0, v137
	v_max_f32_e32 v136, 0, v136
	v_max_f32_e32 v135, 0, v135
	v_max_f32_e32 v134, 0, v134
	v_max_f32_e32 v155, 0, v155
	v_max_f32_e32 v154, 0, v154
	v_max_f32_e32 v139, 0, v139
	v_max_f32_e32 v138, 0, v138
	v_pk_mul_f32 v[156:157], v[134:135], v[134:135]
	v_pk_mul_f32 v[134:135], v[136:137], v[136:137]
	v_pk_mul_f32 v[138:139], v[138:139], v[138:139]
	v_pk_mul_f32 v[136:137], v[154:155], v[154:155]
	v_cvt_pk_bf16_f32 v134, v134, v135
	v_cvt_pk_bf16_f32 v135, v156, v157
	s_nop 0
	v_cvt_pk_bf16_f32 v136, v136, v137
	v_cvt_pk_bf16_f32 v137, v138, v139
	v_add_u32_e32 v138, 0xb0, v132
	v_ashrrev_i32_e32 v139, 31, v138
	global_store_dwordx4 v[140:141], v[134:137], off offset:256
	v_lshl_add_u64 v[132:133], v[138:139], 2, s[96:97]
	v_mov_b32_e32 v112, v195
	v_pk_mul_f32 v[134:135], v[14:15], v[112:113] op_sel_hi:[1,0]
	v_pk_mul_f32 v[136:137], v[12:13], v[112:113] op_sel_hi:[1,0]
	v_pk_mul_f32 v[140:141], v[10:11], v[112:113] op_sel_hi:[1,0]
	v_pk_mul_f32 v[154:155], v[8:9], v[112:113] op_sel_hi:[1,0]
	v_max_f32_e32 v137, 0, v137
	v_max_f32_e32 v136, 0, v136
	v_max_f32_e32 v135, 0, v135
	v_max_f32_e32 v134, 0, v134
	v_max_f32_e32 v155, 0, v155
	v_max_f32_e32 v154, 0, v154
	v_max_f32_e32 v141, 0, v141
	v_max_f32_e32 v140, 0, v140
	v_pk_mul_f32 v[156:157], v[134:135], v[134:135]
	v_pk_mul_f32 v[134:135], v[136:137], v[136:137]
	v_pk_mul_f32 v[140:141], v[140:141], v[140:141]
	v_pk_mul_f32 v[136:137], v[154:155], v[154:155]
	v_cvt_pk_bf16_f32 v134, v134, v135
	v_cvt_pk_bf16_f32 v135, v156, v157
	v_mul_lo_u32 v112, s88, v139
	v_cvt_pk_bf16_f32 v136, v136, v137
	v_cvt_pk_bf16_f32 v137, v140, v141
	v_mul_lo_u32 v140, s89, v138
	v_mad_u64_u32 v[138:139], s[20:21], s88, v138, 0
	v_add3_u32 v139, v139, v112, v140
	v_lshl_add_u64 v[138:139], v[138:139], 1, s[90:91]
	v_lshl_add_u64 v[138:139], v[138:139], 0, v[130:131]
	global_store_dwordx4 v[138:139], v[134:137], off
	v_mov_b32_e32 v112, v195
	s_mov_b64 s[20:21], 0
	v_pk_mul_f32 v[130:131], v[6:7], v[112:113] op_sel_hi:[1,0]
	v_pk_mul_f32 v[132:133], v[4:5], v[112:113] op_sel_hi:[1,0]
	v_pk_mul_f32 v[136:137], v[0:1], v[112:113] op_sel_hi:[1,0]
	v_pk_mul_f32 v[134:135], v[2:3], v[112:113] op_sel_hi:[1,0]
	v_max_f32_e32 v133, 0, v133
	v_max_f32_e32 v132, 0, v132
	v_max_f32_e32 v131, 0, v131
	v_max_f32_e32 v130, 0, v130
	v_max_f32_e32 v137, 0, v137
	v_max_f32_e32 v136, 0, v136
	v_max_f32_e32 v135, 0, v135
	v_max_f32_e32 v134, 0, v134
	v_pk_mul_f32 v[140:141], v[130:131], v[130:131]
	v_pk_mul_f32 v[130:131], v[132:133], v[132:133]
	v_pk_mul_f32 v[132:133], v[136:137], v[136:137]
	v_pk_mul_f32 v[134:135], v[134:135], v[134:135]
	v_cvt_pk_bf16_f32 v130, v130, v131
	v_cvt_pk_bf16_f32 v131, v140, v141
	v_cvt_pk_bf16_f32 v132, v132, v133
	s_nop 0
	v_cvt_pk_bf16_f32 v133, v134, v135
	global_store_dwordx4 v[138:139], v[130:133], off offset:256
